# DPP reductions + gemm_up rms loads batched + phase_modv inner loop unrolled x16 with 16 global loads in flight (bit-identical)
# speedup vs baseline: 1.0025x; 1.0008x over previous
; DEVI void phase_modv(const Params& p, char* lds) {
;     ...
;     for (int k = ks * 128; k < ks * 128 + 128; ++k) {
;       const float w = W[(long)k * 6144];
; #pragma unroll
;       for (int j = 0; j < 9; ++j) a[j] += ca[j * 1024 + k] * w;
.LBB0_87:
	global_load_dword v40, v[8:9], off
	v_lshl_add_u64 v[8:9], v[8:9], 0, s[4:5]
	global_load_dword v41, v[8:9], off
	v_lshl_add_u64 v[8:9], v[8:9], 0, s[4:5]
	global_load_dword v42, v[8:9], off
	v_lshl_add_u64 v[8:9], v[8:9], 0, s[4:5]
	global_load_dword v43, v[8:9], off
	v_lshl_add_u64 v[8:9], v[8:9], 0, s[4:5]
	global_load_dword v44, v[8:9], off
	v_lshl_add_u64 v[8:9], v[8:9], 0, s[4:5]
	global_load_dword v45, v[8:9], off
	v_lshl_add_u64 v[8:9], v[8:9], 0, s[4:5]
	global_load_dword v46, v[8:9], off
	v_lshl_add_u64 v[8:9], v[8:9], 0, s[4:5]
	global_load_dword v47, v[8:9], off
	v_lshl_add_u64 v[8:9], v[8:9], 0, s[4:5]
	global_load_dword v48, v[8:9], off
	v_lshl_add_u64 v[8:9], v[8:9], 0, s[4:5]
	global_load_dword v49, v[8:9], off
	v_lshl_add_u64 v[8:9], v[8:9], 0, s[4:5]
	global_load_dword v50, v[8:9], off
	v_lshl_add_u64 v[8:9], v[8:9], 0, s[4:5]
	global_load_dword v51, v[8:9], off
	v_lshl_add_u64 v[8:9], v[8:9], 0, s[4:5]
	global_load_dword v52, v[8:9], off
	v_lshl_add_u64 v[8:9], v[8:9], 0, s[4:5]
	global_load_dword v53, v[8:9], off
	v_lshl_add_u64 v[8:9], v[8:9], 0, s[4:5]
	global_load_dword v54, v[8:9], off
	v_lshl_add_u64 v[8:9], v[8:9], 0, s[4:5]
	global_load_dword v55, v[8:9], off
	v_lshl_add_u64 v[8:9], v[8:9], 0, s[4:5]
	ds_read2st64_b32 v[28:29], v23 offset1:16
	ds_read2st64_b32 v[30:31], v23 offset0:32 offset1:48
	ds_read2st64_b32 v[32:33], v23 offset0:64 offset1:80
	ds_read2st64_b32 v[34:35], v23 offset0:96 offset1:112
	ds_read_b32 v27, v23 offset:32768
	v_add_u32_e32 v24, 1, v24
	v_add_u32_e32 v23, 4, v23
	s_waitcnt vmcnt(15) lgkmcnt(0)
	v_mov_b32_e32 v26, v40
	v_pk_fma_f32 v[6:7], v[26:27], v[28:29], v[6:7] op_sel_hi:[0,1,1]
	v_pk_fma_f32 v[10:11], v[26:27], v[30:31], v[10:11] op_sel_hi:[0,1,1]
	v_pk_fma_f32 v[12:13], v[26:27], v[32:33], v[12:13] op_sel_hi:[0,1,1]
	v_pk_fma_f32 v[14:15], v[26:27], v[34:35], v[14:15] op_sel_hi:[0,1,1]
	v_fmac_f32_e32 v25, v26, v27
	ds_read2st64_b32 v[28:29], v23 offset1:16
	ds_read2st64_b32 v[30:31], v23 offset0:32 offset1:48
	ds_read2st64_b32 v[32:33], v23 offset0:64 offset1:80
	ds_read2st64_b32 v[34:35], v23 offset0:96 offset1:112
	ds_read_b32 v27, v23 offset:32768
	v_add_u32_e32 v24, 1, v24
	v_add_u32_e32 v23, 4, v23
	s_waitcnt vmcnt(14) lgkmcnt(0)
	v_mov_b32_e32 v26, v41
	v_pk_fma_f32 v[6:7], v[26:27], v[28:29], v[6:7] op_sel_hi:[0,1,1]
	v_pk_fma_f32 v[10:11], v[26:27], v[30:31], v[10:11] op_sel_hi:[0,1,1]
	v_pk_fma_f32 v[12:13], v[26:27], v[32:33], v[12:13] op_sel_hi:[0,1,1]
	v_pk_fma_f32 v[14:15], v[26:27], v[34:35], v[14:15] op_sel_hi:[0,1,1]
	v_fmac_f32_e32 v25, v26, v27
	ds_read2st64_b32 v[28:29], v23 offset1:16
	ds_read2st64_b32 v[30:31], v23 offset0:32 offset1:48
	ds_read2st64_b32 v[32:33], v23 offset0:64 offset1:80
	ds_read2st64_b32 v[34:35], v23 offset0:96 offset1:112
	ds_read_b32 v27, v23 offset:32768
	v_add_u32_e32 v24, 1, v24
	v_add_u32_e32 v23, 4, v23
	s_waitcnt vmcnt(13) lgkmcnt(0)
	v_mov_b32_e32 v26, v42
	v_pk_fma_f32 v[6:7], v[26:27], v[28:29], v[6:7] op_sel_hi:[0,1,1]
	v_pk_fma_f32 v[10:11], v[26:27], v[30:31], v[10:11] op_sel_hi:[0,1,1]
	v_pk_fma_f32 v[12:13], v[26:27], v[32:33], v[12:13] op_sel_hi:[0,1,1]
	v_pk_fma_f32 v[14:15], v[26:27], v[34:35], v[14:15] op_sel_hi:[0,1,1]
	v_fmac_f32_e32 v25, v26, v27
	ds_read2st64_b32 v[28:29], v23 offset1:16
	ds_read2st64_b32 v[30:31], v23 offset0:32 offset1:48
	ds_read2st64_b32 v[32:33], v23 offset0:64 offset1:80
	ds_read2st64_b32 v[34:35], v23 offset0:96 offset1:112
	ds_read_b32 v27, v23 offset:32768
	v_add_u32_e32 v24, 1, v24
	v_add_u32_e32 v23, 4, v23
	s_waitcnt vmcnt(12) lgkmcnt(0)
	v_mov_b32_e32 v26, v43
	v_pk_fma_f32 v[6:7], v[26:27], v[28:29], v[6:7] op_sel_hi:[0,1,1]
	v_pk_fma_f32 v[10:11], v[26:27], v[30:31], v[10:11] op_sel_hi:[0,1,1]
	v_pk_fma_f32 v[12:13], v[26:27], v[32:33], v[12:13] op_sel_hi:[0,1,1]
	v_pk_fma_f32 v[14:15], v[26:27], v[34:35], v[14:15] op_sel_hi:[0,1,1]
	v_fmac_f32_e32 v25, v26, v27
	ds_read2st64_b32 v[28:29], v23 offset1:16
	ds_read2st64_b32 v[30:31], v23 offset0:32 offset1:48
	ds_read2st64_b32 v[32:33], v23 offset0:64 offset1:80
	ds_read2st64_b32 v[34:35], v23 offset0:96 offset1:112
	ds_read_b32 v27, v23 offset:32768
	v_add_u32_e32 v24, 1, v24
	v_add_u32_e32 v23, 4, v23
	s_waitcnt vmcnt(11) lgkmcnt(0)
	v_mov_b32_e32 v26, v44
	v_pk_fma_f32 v[6:7], v[26:27], v[28:29], v[6:7] op_sel_hi:[0,1,1]
	v_pk_fma_f32 v[10:11], v[26:27], v[30:31], v[10:11] op_sel_hi:[0,1,1]
	v_pk_fma_f32 v[12:13], v[26:27], v[32:33], v[12:13] op_sel_hi:[0,1,1]
	v_pk_fma_f32 v[14:15], v[26:27], v[34:35], v[14:15] op_sel_hi:[0,1,1]
	v_fmac_f32_e32 v25, v26, v27
	ds_read2st64_b32 v[28:29], v23 offset1:16
	ds_read2st64_b32 v[30:31], v23 offset0:32 offset1:48
	ds_read2st64_b32 v[32:33], v23 offset0:64 offset1:80
	ds_read2st64_b32 v[34:35], v23 offset0:96 offset1:112
	ds_read_b32 v27, v23 offset:32768
	v_add_u32_e32 v24, 1, v24
	v_add_u32_e32 v23, 4, v23
	s_waitcnt vmcnt(10) lgkmcnt(0)
	v_mov_b32_e32 v26, v45
	v_pk_fma_f32 v[6:7], v[26:27], v[28:29], v[6:7] op_sel_hi:[0,1,1]
	v_pk_fma_f32 v[10:11], v[26:27], v[30:31], v[10:11] op_sel_hi:[0,1,1]
	v_pk_fma_f32 v[12:13], v[26:27], v[32:33], v[12:13] op_sel_hi:[0,1,1]
	v_pk_fma_f32 v[14:15], v[26:27], v[34:35], v[14:15] op_sel_hi:[0,1,1]
	v_fmac_f32_e32 v25, v26, v27
	ds_read2st64_b32 v[28:29], v23 offset1:16
	ds_read2st64_b32 v[30:31], v23 offset0:32 offset1:48
	ds_read2st64_b32 v[32:33], v23 offset0:64 offset1:80
	ds_read2st64_b32 v[34:35], v23 offset0:96 offset1:112
	ds_read_b32 v27, v23 offset:32768
	v_add_u32_e32 v24, 1, v24
	v_add_u32_e32 v23, 4, v23
	s_waitcnt vmcnt(9) lgkmcnt(0)
; DEVI void phase_modv(const Params& p, char* lds) {
;     ...
;     for (int k = ks * 128; k < ks * 128 + 128; ++k) {
;       const float w = W[(long)k * 6144];
; #pragma unroll
;       for (int j = 0; j < 9; ++j) a[j] += ca[j * 1024 + k] * w;
;     }
; #pragma unroll
;     for (int j = 0; j < 9; ++j) red[(ks * 64 + col) * 9 + j] = a[j];
;     __syncthreads();
;     for (int i = tid; i < 64 * 9; i += NTHREADS) {
	v_mov_b32_e32 v26, v46
	v_pk_fma_f32 v[6:7], v[26:27], v[28:29], v[6:7] op_sel_hi:[0,1,1]
	v_pk_fma_f32 v[10:11], v[26:27], v[30:31], v[10:11] op_sel_hi:[0,1,1]
	v_pk_fma_f32 v[12:13], v[26:27], v[32:33], v[12:13] op_sel_hi:[0,1,1]
	v_pk_fma_f32 v[14:15], v[26:27], v[34:35], v[14:15] op_sel_hi:[0,1,1]
	v_fmac_f32_e32 v25, v26, v27
	ds_read2st64_b32 v[28:29], v23 offset1:16
	ds_read2st64_b32 v[30:31], v23 offset0:32 offset1:48
	ds_read2st64_b32 v[32:33], v23 offset0:64 offset1:80
	ds_read2st64_b32 v[34:35], v23 offset0:96 offset1:112
	ds_read_b32 v27, v23 offset:32768
	v_add_u32_e32 v24, 1, v24
	v_add_u32_e32 v23, 4, v23
	s_waitcnt vmcnt(8) lgkmcnt(0)
	v_mov_b32_e32 v26, v47
	v_pk_fma_f32 v[6:7], v[26:27], v[28:29], v[6:7] op_sel_hi:[0,1,1]
	v_pk_fma_f32 v[10:11], v[26:27], v[30:31], v[10:11] op_sel_hi:[0,1,1]
	v_pk_fma_f32 v[12:13], v[26:27], v[32:33], v[12:13] op_sel_hi:[0,1,1]
	v_pk_fma_f32 v[14:15], v[26:27], v[34:35], v[14:15] op_sel_hi:[0,1,1]
	v_fmac_f32_e32 v25, v26, v27
	ds_read2st64_b32 v[28:29], v23 offset1:16
	ds_read2st64_b32 v[30:31], v23 offset0:32 offset1:48
	ds_read2st64_b32 v[32:33], v23 offset0:64 offset1:80
	ds_read2st64_b32 v[34:35], v23 offset0:96 offset1:112
	ds_read_b32 v27, v23 offset:32768
	v_add_u32_e32 v24, 1, v24
	v_add_u32_e32 v23, 4, v23
	s_waitcnt vmcnt(7) lgkmcnt(0)
	v_mov_b32_e32 v26, v48
	v_pk_fma_f32 v[6:7], v[26:27], v[28:29], v[6:7] op_sel_hi:[0,1,1]
	v_pk_fma_f32 v[10:11], v[26:27], v[30:31], v[10:11] op_sel_hi:[0,1,1]
	v_pk_fma_f32 v[12:13], v[26:27], v[32:33], v[12:13] op_sel_hi:[0,1,1]
	v_pk_fma_f32 v[14:15], v[26:27], v[34:35], v[14:15] op_sel_hi:[0,1,1]
	v_fmac_f32_e32 v25, v26, v27
	ds_read2st64_b32 v[28:29], v23 offset1:16
	ds_read2st64_b32 v[30:31], v23 offset0:32 offset1:48
	ds_read2st64_b32 v[32:33], v23 offset0:64 offset1:80
	ds_read2st64_b32 v[34:35], v23 offset0:96 offset1:112
	ds_read_b32 v27, v23 offset:32768
	v_add_u32_e32 v24, 1, v24
	v_add_u32_e32 v23, 4, v23
	s_waitcnt vmcnt(6) lgkmcnt(0)
	v_mov_b32_e32 v26, v49
	v_pk_fma_f32 v[6:7], v[26:27], v[28:29], v[6:7] op_sel_hi:[0,1,1]
	v_pk_fma_f32 v[10:11], v[26:27], v[30:31], v[10:11] op_sel_hi:[0,1,1]
	v_pk_fma_f32 v[12:13], v[26:27], v[32:33], v[12:13] op_sel_hi:[0,1,1]
	v_pk_fma_f32 v[14:15], v[26:27], v[34:35], v[14:15] op_sel_hi:[0,1,1]
	v_fmac_f32_e32 v25, v26, v27
	ds_read2st64_b32 v[28:29], v23 offset1:16
	ds_read2st64_b32 v[30:31], v23 offset0:32 offset1:48
	ds_read2st64_b32 v[32:33], v23 offset0:64 offset1:80
	ds_read2st64_b32 v[34:35], v23 offset0:96 offset1:112
	ds_read_b32 v27, v23 offset:32768
	v_add_u32_e32 v24, 1, v24
	v_add_u32_e32 v23, 4, v23
	s_waitcnt vmcnt(5) lgkmcnt(0)
	v_mov_b32_e32 v26, v50
	v_pk_fma_f32 v[6:7], v[26:27], v[28:29], v[6:7] op_sel_hi:[0,1,1]
	v_pk_fma_f32 v[10:11], v[26:27], v[30:31], v[10:11] op_sel_hi:[0,1,1]
	v_pk_fma_f32 v[12:13], v[26:27], v[32:33], v[12:13] op_sel_hi:[0,1,1]
	v_pk_fma_f32 v[14:15], v[26:27], v[34:35], v[14:15] op_sel_hi:[0,1,1]
	v_fmac_f32_e32 v25, v26, v27
	ds_read2st64_b32 v[28:29], v23 offset1:16
	ds_read2st64_b32 v[30:31], v23 offset0:32 offset1:48
	ds_read2st64_b32 v[32:33], v23 offset0:64 offset1:80
	ds_read2st64_b32 v[34:35], v23 offset0:96 offset1:112
	ds_read_b32 v27, v23 offset:32768
	v_add_u32_e32 v24, 1, v24
	v_add_u32_e32 v23, 4, v23
	s_waitcnt vmcnt(4) lgkmcnt(0)
	v_mov_b32_e32 v26, v51
	v_pk_fma_f32 v[6:7], v[26:27], v[28:29], v[6:7] op_sel_hi:[0,1,1]
	v_pk_fma_f32 v[10:11], v[26:27], v[30:31], v[10:11] op_sel_hi:[0,1,1]
	v_pk_fma_f32 v[12:13], v[26:27], v[32:33], v[12:13] op_sel_hi:[0,1,1]
	v_pk_fma_f32 v[14:15], v[26:27], v[34:35], v[14:15] op_sel_hi:[0,1,1]
	v_fmac_f32_e32 v25, v26, v27
	ds_read2st64_b32 v[28:29], v23 offset1:16
	ds_read2st64_b32 v[30:31], v23 offset0:32 offset1:48
	ds_read2st64_b32 v[32:33], v23 offset0:64 offset1:80
	ds_read2st64_b32 v[34:35], v23 offset0:96 offset1:112
	ds_read_b32 v27, v23 offset:32768
	v_add_u32_e32 v24, 1, v24
	v_add_u32_e32 v23, 4, v23
	s_waitcnt vmcnt(3) lgkmcnt(0)
	v_mov_b32_e32 v26, v52
	v_pk_fma_f32 v[6:7], v[26:27], v[28:29], v[6:7] op_sel_hi:[0,1,1]
	v_pk_fma_f32 v[10:11], v[26:27], v[30:31], v[10:11] op_sel_hi:[0,1,1]
	v_pk_fma_f32 v[12:13], v[26:27], v[32:33], v[12:13] op_sel_hi:[0,1,1]
	v_pk_fma_f32 v[14:15], v[26:27], v[34:35], v[14:15] op_sel_hi:[0,1,1]
	v_fmac_f32_e32 v25, v26, v27
	ds_read2st64_b32 v[28:29], v23 offset1:16
	ds_read2st64_b32 v[30:31], v23 offset0:32 offset1:48
	ds_read2st64_b32 v[32:33], v23 offset0:64 offset1:80
	ds_read2st64_b32 v[34:35], v23 offset0:96 offset1:112
	ds_read_b32 v27, v23 offset:32768
	v_add_u32_e32 v24, 1, v24
	v_add_u32_e32 v23, 4, v23
	s_waitcnt vmcnt(2) lgkmcnt(0)
	v_mov_b32_e32 v26, v53
	v_pk_fma_f32 v[6:7], v[26:27], v[28:29], v[6:7] op_sel_hi:[0,1,1]
	v_pk_fma_f32 v[10:11], v[26:27], v[30:31], v[10:11] op_sel_hi:[0,1,1]
	v_pk_fma_f32 v[12:13], v[26:27], v[32:33], v[12:13] op_sel_hi:[0,1,1]
	v_pk_fma_f32 v[14:15], v[26:27], v[34:35], v[14:15] op_sel_hi:[0,1,1]
	v_fmac_f32_e32 v25, v26, v27
	ds_read2st64_b32 v[28:29], v23 offset1:16
	ds_read2st64_b32 v[30:31], v23 offset0:32 offset1:48
	ds_read2st64_b32 v[32:33], v23 offset0:64 offset1:80
	ds_read2st64_b32 v[34:35], v23 offset0:96 offset1:112
	ds_read_b32 v27, v23 offset:32768
	v_add_u32_e32 v24, 1, v24
	v_add_u32_e32 v23, 4, v23
	s_waitcnt vmcnt(1) lgkmcnt(0)
	v_mov_b32_e32 v26, v54
	v_pk_fma_f32 v[6:7], v[26:27], v[28:29], v[6:7] op_sel_hi:[0,1,1]
	v_pk_fma_f32 v[10:11], v[26:27], v[30:31], v[10:11] op_sel_hi:[0,1,1]
	v_pk_fma_f32 v[12:13], v[26:27], v[32:33], v[12:13] op_sel_hi:[0,1,1]
	v_pk_fma_f32 v[14:15], v[26:27], v[34:35], v[14:15] op_sel_hi:[0,1,1]
	v_fmac_f32_e32 v25, v26, v27
	ds_read2st64_b32 v[28:29], v23 offset1:16
	ds_read2st64_b32 v[30:31], v23 offset0:32 offset1:48
	ds_read2st64_b32 v[32:33], v23 offset0:64 offset1:80
	ds_read2st64_b32 v[34:35], v23 offset0:96 offset1:112
	ds_read_b32 v27, v23 offset:32768
	v_add_u32_e32 v24, 1, v24
	v_add_u32_e32 v23, 4, v23
	v_cmp_ge_i32_e64 s[0:1], v24, v1
	s_waitcnt vmcnt(0) lgkmcnt(0)
	v_mov_b32_e32 v26, v55
	v_pk_fma_f32 v[6:7], v[26:27], v[28:29], v[6:7] op_sel_hi:[0,1,1]
	v_pk_fma_f32 v[10:11], v[26:27], v[30:31], v[10:11] op_sel_hi:[0,1,1]
	v_pk_fma_f32 v[12:13], v[26:27], v[32:33], v[12:13] op_sel_hi:[0,1,1]
	v_pk_fma_f32 v[14:15], v[26:27], v[34:35], v[14:15] op_sel_hi:[0,1,1]
	v_fmac_f32_e32 v25, v26, v27
	s_or_b64 s[10:11], s[0:1], s[10:11]
	s_andn2_b64 exec, exec, s[10:11]
	s_cbranch_execnz .LBB0_87
	s_or_b64 exec, exec, s[10:11]
	ds_write2_b32 v19, v6, v7 offset1:1
	ds_write2_b32 v20, v10, v11 offset1:1
	ds_write2_b32 v21, v12, v13 offset1:1
	ds_write2_b32 v22, v14, v15 offset1:1
	ds_write_b32 v18, v25 offset:36896
	s_waitcnt lgkmcnt(0)
	s_barrier
	s_and_saveexec_b64 s[10:11], vcc
	s_cbranch_execz .LBB0_85
	v_readlane_b32 s0, v252, 43
	v_readlane_b32 s1, v252, 44
	s_add_u32 s8, s0, s8
	s_mul_i32 s16, s12, 0x1800
	s_addc_u32 s9, s1, s9
	s_add_i32 s16, s16, s6
	s_mul_hi_i32 s7, s12, 9
	s_mul_i32 s6, s12, 9
	s_mov_b64 s[12:13], 0
	v_mov_b32_e32 v7, v17
	v_mov_b32_e32 v6, v2
